# adds: phase-0 modulation partials load all 64 weight rows of an item up front (was 4 loads per iteration with a full drain)
# speedup vs baseline: 1.0141x; 1.0008x over previous
.LBB0_22:
	s_or_b64 exec, exec, s[4:5]
	s_load_dwordx16 s[72:87], s[0:1], 0xc0
	s_mul_i32 s23, s23, 18
	s_sub_i32 s6, s19, s23
	s_add_i32 s4, s19, 0x11f
	s_cmpk_lt_u32 s4, 0x23f
	s_mul_i32 s4, s22, 0x90000
	s_waitcnt lgkmcnt(0)
	s_cselect_b32 s7, s67, s75
	s_cselect_b32 s23, s66, s74
	s_ashr_i32 s5, s4, 31
	s_lshl_b64 s[4:5], s[4:5], 2
	s_add_u32 s23, s23, s4
	s_addc_u32 s7, s7, s5
	s_lshl_b32 s4, s6, 9
	s_ashr_i32 s5, s4, 31
	s_lshl_b64 s[4:5], s[4:5], 2
	s_add_u32 s6, s23, s4
	s_addc_u32 s7, s7, s5
	v_mov_b32_e32 v8, 0
	v_lshl_add_u64 v[10:11], v[0:1], 2, s[6:7]
	s_mov_b64 s[98:99], s[6:7]
	s_mov_b64 s[6:7], 0
	s_mov_b32 s23, 0
	v_mov_b32_e32 v9, v8
	v_mov_b32_e32 v6, v8
	v_mov_b32_e32 v7, v8
	v_mov_b32_e32 v4, v8
	v_mov_b32_e32 v5, v8
	v_mov_b32_e32 v2, v8
	v_mov_b32_e32 v3, v8
	v_mov_b32_e32 v13, v8
	global_load_dword v66, v12, s[98:99]
	s_add_u32 s98, s98, s13
	s_addc_u32 s99, s99, 0
	global_load_dword v67, v12, s[98:99]
	s_add_u32 s98, s98, s13
	s_addc_u32 s99, s99, 0
	global_load_dword v68, v12, s[98:99]
	s_add_u32 s98, s98, s13
	s_addc_u32 s99, s99, 0
	global_load_dword v69, v12, s[98:99]
	s_add_u32 s98, s98, s13
	s_addc_u32 s99, s99, 0
	global_load_dword v70, v12, s[98:99]
	s_add_u32 s98, s98, s13
	s_addc_u32 s99, s99, 0
	global_load_dword v71, v12, s[98:99]
	s_add_u32 s98, s98, s13
	s_addc_u32 s99, s99, 0
	global_load_dword v72, v12, s[98:99]
	s_add_u32 s98, s98, s13
	s_addc_u32 s99, s99, 0
	global_load_dword v73, v12, s[98:99]
	s_add_u32 s98, s98, s13
	s_addc_u32 s99, s99, 0
	global_load_dword v74, v12, s[98:99]
	s_add_u32 s98, s98, s13
	s_addc_u32 s99, s99, 0
	global_load_dword v75, v12, s[98:99]
	s_add_u32 s98, s98, s13
	s_addc_u32 s99, s99, 0
	global_load_dword v76, v12, s[98:99]
	s_add_u32 s98, s98, s13
	s_addc_u32 s99, s99, 0
	global_load_dword v77, v12, s[98:99]
	s_add_u32 s98, s98, s13
	s_addc_u32 s99, s99, 0
	global_load_dword v78, v12, s[98:99]
	s_add_u32 s98, s98, s13
	s_addc_u32 s99, s99, 0
	global_load_dword v79, v12, s[98:99]
	s_add_u32 s98, s98, s13
	s_addc_u32 s99, s99, 0
	global_load_dword v80, v12, s[98:99]
	s_add_u32 s98, s98, s13
	s_addc_u32 s99, s99, 0
	global_load_dword v81, v12, s[98:99]
	s_add_u32 s98, s98, s13
	s_addc_u32 s99, s99, 0
	global_load_dword v82, v12, s[98:99]
	s_add_u32 s98, s98, s13
	s_addc_u32 s99, s99, 0
	global_load_dword v83, v12, s[98:99]
	s_add_u32 s98, s98, s13
	s_addc_u32 s99, s99, 0
	global_load_dword v84, v12, s[98:99]
	s_add_u32 s98, s98, s13
	s_addc_u32 s99, s99, 0
	global_load_dword v85, v12, s[98:99]
	s_add_u32 s98, s98, s13
	s_addc_u32 s99, s99, 0
	global_load_dword v86, v12, s[98:99]
	s_add_u32 s98, s98, s13
	s_addc_u32 s99, s99, 0
	global_load_dword v87, v12, s[98:99]
	s_add_u32 s98, s98, s13
	s_addc_u32 s99, s99, 0
	global_load_dword v88, v12, s[98:99]
	s_add_u32 s98, s98, s13
	s_addc_u32 s99, s99, 0
	global_load_dword v89, v12, s[98:99]
	s_add_u32 s98, s98, s13
	s_addc_u32 s99, s99, 0
	global_load_dword v90, v12, s[98:99]
	s_add_u32 s98, s98, s13
	s_addc_u32 s99, s99, 0
	global_load_dword v91, v12, s[98:99]
	s_add_u32 s98, s98, s13
	s_addc_u32 s99, s99, 0
	global_load_dword v92, v12, s[98:99]
	s_add_u32 s98, s98, s13
	s_addc_u32 s99, s99, 0
	global_load_dword v93, v12, s[98:99]
	s_add_u32 s98, s98, s13
	s_addc_u32 s99, s99, 0
	global_load_dword v94, v12, s[98:99]
	s_add_u32 s98, s98, s13
	s_addc_u32 s99, s99, 0
	global_load_dword v95, v12, s[98:99]
	s_add_u32 s98, s98, s13
	s_addc_u32 s99, s99, 0
	global_load_dword v96, v12, s[98:99]
	s_add_u32 s98, s98, s13
	s_addc_u32 s99, s99, 0
	global_load_dword v97, v12, s[98:99]
	s_add_u32 s98, s98, s13
	s_addc_u32 s99, s99, 0
	global_load_dword v98, v12, s[98:99]
	s_add_u32 s98, s98, s13
	s_addc_u32 s99, s99, 0
	global_load_dword v99, v12, s[98:99]
	s_add_u32 s98, s98, s13
	s_addc_u32 s99, s99, 0
	global_load_dword v100, v12, s[98:99]
	s_add_u32 s98, s98, s13
	s_addc_u32 s99, s99, 0
	global_load_dword v101, v12, s[98:99]
	s_add_u32 s98, s98, s13
	s_addc_u32 s99, s99, 0
	global_load_dword v102, v12, s[98:99]
	s_add_u32 s98, s98, s13
	s_addc_u32 s99, s99, 0
	global_load_dword v103, v12, s[98:99]
	s_add_u32 s98, s98, s13
	s_addc_u32 s99, s99, 0
	global_load_dword v104, v12, s[98:99]
	s_add_u32 s98, s98, s13
	s_addc_u32 s99, s99, 0
	global_load_dword v105, v12, s[98:99]
	s_add_u32 s98, s98, s13
	s_addc_u32 s99, s99, 0
	global_load_dword v106, v12, s[98:99]
	s_add_u32 s98, s98, s13
	s_addc_u32 s99, s99, 0
	global_load_dword v107, v12, s[98:99]
	s_add_u32 s98, s98, s13
	s_addc_u32 s99, s99, 0
	global_load_dword v108, v12, s[98:99]
	s_add_u32 s98, s98, s13
	s_addc_u32 s99, s99, 0
	global_load_dword v109, v12, s[98:99]
	s_add_u32 s98, s98, s13
	s_addc_u32 s99, s99, 0
	global_load_dword v110, v12, s[98:99]
	s_add_u32 s98, s98, s13
	s_addc_u32 s99, s99, 0
	global_load_dword v111, v12, s[98:99]
	s_add_u32 s98, s98, s13
	s_addc_u32 s99, s99, 0
	global_load_dword v112, v12, s[98:99]
	s_add_u32 s98, s98, s13
	s_addc_u32 s99, s99, 0
	global_load_dword v113, v12, s[98:99]
	s_add_u32 s98, s98, s13
	s_addc_u32 s99, s99, 0
	global_load_dword v114, v12, s[98:99]
	s_add_u32 s98, s98, s13
	s_addc_u32 s99, s99, 0
	global_load_dword v115, v12, s[98:99]
	s_add_u32 s98, s98, s13
	s_addc_u32 s99, s99, 0
	global_load_dword v116, v12, s[98:99]
	s_add_u32 s98, s98, s13
	s_addc_u32 s99, s99, 0
	global_load_dword v117, v12, s[98:99]
	s_add_u32 s98, s98, s13
	s_addc_u32 s99, s99, 0
	global_load_dword v118, v12, s[98:99]
	s_add_u32 s98, s98, s13
	s_addc_u32 s99, s99, 0
	global_load_dword v119, v12, s[98:99]
	s_add_u32 s98, s98, s13
	s_addc_u32 s99, s99, 0
	global_load_dword v120, v12, s[98:99]
	s_add_u32 s98, s98, s13
	s_addc_u32 s99, s99, 0
	global_load_dword v121, v12, s[98:99]
	s_add_u32 s98, s98, s13
	s_addc_u32 s99, s99, 0
	s_barrier
	v_mov_b32_e32 v65, 0
	ds_read_b128 v[14:17], v65 offset:0
	ds_read_b128 v[18:21], v65 offset:256
	ds_read_b128 v[22:25], v65 offset:512
	ds_read_b128 v[26:29], v65 offset:768
	ds_read_b128 v[30:33], v65 offset:1024
	ds_read_b128 v[34:37], v65 offset:1280
	ds_read_b128 v[38:41], v65 offset:1536
	ds_read_b128 v[42:45], v65 offset:1792
	ds_read_b128 v[46:49], v65 offset:2048
	s_waitcnt lgkmcnt(0)
	ds_read_b128 v[130:133], v65 offset:16
	ds_read_b128 v[134:137], v65 offset:272
	ds_read_b128 v[138:141], v65 offset:528
	ds_read_b128 v[142:145], v65 offset:784
	ds_read_b128 v[146:149], v65 offset:1040
	ds_read_b128 v[150:153], v65 offset:1296
	ds_read_b128 v[154:157], v65 offset:1552
	ds_read_b128 v[158:161], v65 offset:1808
	ds_read_b128 v[162:165], v65 offset:2064
	s_waitcnt vmcnt(55)
	v_fmac_f32_e32 v8, v66, v14
	v_fmac_f32_e32 v9, v66, v18
	v_fmac_f32_e32 v6, v66, v22
	v_fmac_f32_e32 v7, v66, v26
	v_fmac_f32_e32 v4, v66, v30
	v_fmac_f32_e32 v5, v66, v34
	v_fmac_f32_e32 v2, v66, v38
	v_fmac_f32_e32 v3, v66, v42
	v_fmac_f32_e32 v13, v66, v46
	s_waitcnt vmcnt(54)
	v_fmac_f32_e32 v8, v67, v15
	v_fmac_f32_e32 v9, v67, v19
	v_fmac_f32_e32 v6, v67, v23
	v_fmac_f32_e32 v7, v67, v27
	v_fmac_f32_e32 v4, v67, v31
	v_fmac_f32_e32 v5, v67, v35
	v_fmac_f32_e32 v2, v67, v39
	v_fmac_f32_e32 v3, v67, v43
	v_fmac_f32_e32 v13, v67, v47
	s_waitcnt vmcnt(53)
	v_fmac_f32_e32 v8, v68, v16
	v_fmac_f32_e32 v9, v68, v20
	v_fmac_f32_e32 v6, v68, v24
	v_fmac_f32_e32 v7, v68, v28
	v_fmac_f32_e32 v4, v68, v32
	v_fmac_f32_e32 v5, v68, v36
	v_fmac_f32_e32 v2, v68, v40
	v_fmac_f32_e32 v3, v68, v44
	v_fmac_f32_e32 v13, v68, v48
	s_waitcnt vmcnt(52)
	v_fmac_f32_e32 v8, v69, v17
	v_fmac_f32_e32 v9, v69, v21
	v_fmac_f32_e32 v6, v69, v25
	v_fmac_f32_e32 v7, v69, v29
	v_fmac_f32_e32 v4, v69, v33
	v_fmac_f32_e32 v5, v69, v37
	v_fmac_f32_e32 v2, v69, v41
	v_fmac_f32_e32 v3, v69, v45
	v_fmac_f32_e32 v13, v69, v49
	s_waitcnt lgkmcnt(0)
	ds_read_b128 v[14:17], v65 offset:32
	ds_read_b128 v[18:21], v65 offset:288
	ds_read_b128 v[22:25], v65 offset:544
	ds_read_b128 v[26:29], v65 offset:800
	ds_read_b128 v[30:33], v65 offset:1056
	ds_read_b128 v[34:37], v65 offset:1312
	ds_read_b128 v[38:41], v65 offset:1568
	ds_read_b128 v[42:45], v65 offset:1824
	ds_read_b128 v[46:49], v65 offset:2080
	s_waitcnt vmcnt(51)
	v_fmac_f32_e32 v8, v70, v130
	v_fmac_f32_e32 v9, v70, v134
	v_fmac_f32_e32 v6, v70, v138
	v_fmac_f32_e32 v7, v70, v142
	v_fmac_f32_e32 v4, v70, v146
	v_fmac_f32_e32 v5, v70, v150
	v_fmac_f32_e32 v2, v70, v154
	v_fmac_f32_e32 v3, v70, v158
	v_fmac_f32_e32 v13, v70, v162
	s_waitcnt vmcnt(50)
	v_fmac_f32_e32 v8, v71, v131
	v_fmac_f32_e32 v9, v71, v135
	v_fmac_f32_e32 v6, v71, v139
	v_fmac_f32_e32 v7, v71, v143
	v_fmac_f32_e32 v4, v71, v147
	v_fmac_f32_e32 v5, v71, v151
	v_fmac_f32_e32 v2, v71, v155
	v_fmac_f32_e32 v3, v71, v159
	v_fmac_f32_e32 v13, v71, v163
	s_waitcnt vmcnt(49)
	v_fmac_f32_e32 v8, v72, v132
	v_fmac_f32_e32 v9, v72, v136
	v_fmac_f32_e32 v6, v72, v140
	v_fmac_f32_e32 v7, v72, v144
	v_fmac_f32_e32 v4, v72, v148
	v_fmac_f32_e32 v5, v72, v152
	v_fmac_f32_e32 v2, v72, v156
	v_fmac_f32_e32 v3, v72, v160
	v_fmac_f32_e32 v13, v72, v164
	s_waitcnt vmcnt(48)
	v_fmac_f32_e32 v8, v73, v133
	v_fmac_f32_e32 v9, v73, v137
	v_fmac_f32_e32 v6, v73, v141
	v_fmac_f32_e32 v7, v73, v145
	v_fmac_f32_e32 v4, v73, v149
	v_fmac_f32_e32 v5, v73, v153
	v_fmac_f32_e32 v2, v73, v157
	v_fmac_f32_e32 v3, v73, v161
	v_fmac_f32_e32 v13, v73, v165
	global_load_dword v122, v12, s[98:99]
	s_add_u32 s98, s98, s13
	s_addc_u32 s99, s99, 0
	global_load_dword v123, v12, s[98:99]
	s_add_u32 s98, s98, s13
	s_addc_u32 s99, s99, 0
	global_load_dword v124, v12, s[98:99]
	s_add_u32 s98, s98, s13
	s_addc_u32 s99, s99, 0
	global_load_dword v125, v12, s[98:99]
	s_add_u32 s98, s98, s13
	s_addc_u32 s99, s99, 0
	global_load_dword v126, v12, s[98:99]
	s_add_u32 s98, s98, s13
	s_addc_u32 s99, s99, 0
	global_load_dword v127, v12, s[98:99]
	s_add_u32 s98, s98, s13
	s_addc_u32 s99, s99, 0
	global_load_dword v128, v12, s[98:99]
	s_add_u32 s98, s98, s13
	s_addc_u32 s99, s99, 0
	global_load_dword v129, v12, s[98:99]
	s_add_u32 s98, s98, s13
	s_addc_u32 s99, s99, 0
	s_waitcnt lgkmcnt(0)
	ds_read_b128 v[130:133], v65 offset:48
	ds_read_b128 v[134:137], v65 offset:304
	ds_read_b128 v[138:141], v65 offset:560
	ds_read_b128 v[142:145], v65 offset:816
	ds_read_b128 v[146:149], v65 offset:1072
	ds_read_b128 v[150:153], v65 offset:1328
	ds_read_b128 v[154:157], v65 offset:1584
	ds_read_b128 v[158:161], v65 offset:1840
	ds_read_b128 v[162:165], v65 offset:2096
	s_waitcnt vmcnt(55)
	v_fmac_f32_e32 v8, v74, v14
	v_fmac_f32_e32 v9, v74, v18
	v_fmac_f32_e32 v6, v74, v22
	v_fmac_f32_e32 v7, v74, v26
	v_fmac_f32_e32 v4, v74, v30
	v_fmac_f32_e32 v5, v74, v34
	v_fmac_f32_e32 v2, v74, v38
	v_fmac_f32_e32 v3, v74, v42
	v_fmac_f32_e32 v13, v74, v46
	s_waitcnt vmcnt(54)
	v_fmac_f32_e32 v8, v75, v15
	v_fmac_f32_e32 v9, v75, v19
	v_fmac_f32_e32 v6, v75, v23
	v_fmac_f32_e32 v7, v75, v27
	v_fmac_f32_e32 v4, v75, v31
	v_fmac_f32_e32 v5, v75, v35
	v_fmac_f32_e32 v2, v75, v39
	v_fmac_f32_e32 v3, v75, v43
	v_fmac_f32_e32 v13, v75, v47
	s_waitcnt vmcnt(53)
	v_fmac_f32_e32 v8, v76, v16
	v_fmac_f32_e32 v9, v76, v20
	v_fmac_f32_e32 v6, v76, v24
	v_fmac_f32_e32 v7, v76, v28
	v_fmac_f32_e32 v4, v76, v32
	v_fmac_f32_e32 v5, v76, v36
	v_fmac_f32_e32 v2, v76, v40
	v_fmac_f32_e32 v3, v76, v44
	v_fmac_f32_e32 v13, v76, v48
	s_waitcnt vmcnt(52)
	v_fmac_f32_e32 v8, v77, v17
	v_fmac_f32_e32 v9, v77, v21
	v_fmac_f32_e32 v6, v77, v25
	v_fmac_f32_e32 v7, v77, v29
	v_fmac_f32_e32 v4, v77, v33
	v_fmac_f32_e32 v5, v77, v37
	v_fmac_f32_e32 v2, v77, v41
	v_fmac_f32_e32 v3, v77, v45
	v_fmac_f32_e32 v13, v77, v49
	s_waitcnt lgkmcnt(0)
	ds_read_b128 v[14:17], v65 offset:64
	ds_read_b128 v[18:21], v65 offset:320
	ds_read_b128 v[22:25], v65 offset:576
	ds_read_b128 v[26:29], v65 offset:832
	ds_read_b128 v[30:33], v65 offset:1088
	ds_read_b128 v[34:37], v65 offset:1344
	ds_read_b128 v[38:41], v65 offset:1600
	ds_read_b128 v[42:45], v65 offset:1856
	ds_read_b128 v[46:49], v65 offset:2112
	s_waitcnt vmcnt(51)
	v_fmac_f32_e32 v8, v78, v130
	v_fmac_f32_e32 v9, v78, v134
	v_fmac_f32_e32 v6, v78, v138
	v_fmac_f32_e32 v7, v78, v142
	v_fmac_f32_e32 v4, v78, v146
	v_fmac_f32_e32 v5, v78, v150
	v_fmac_f32_e32 v2, v78, v154
	v_fmac_f32_e32 v3, v78, v158
	v_fmac_f32_e32 v13, v78, v162
	s_waitcnt vmcnt(50)
	v_fmac_f32_e32 v8, v79, v131
	v_fmac_f32_e32 v9, v79, v135
	v_fmac_f32_e32 v6, v79, v139
	v_fmac_f32_e32 v7, v79, v143
	v_fmac_f32_e32 v4, v79, v147
	v_fmac_f32_e32 v5, v79, v151
	v_fmac_f32_e32 v2, v79, v155
	v_fmac_f32_e32 v3, v79, v159
	v_fmac_f32_e32 v13, v79, v163
	s_waitcnt vmcnt(49)
	v_fmac_f32_e32 v8, v80, v132
	v_fmac_f32_e32 v9, v80, v136
	v_fmac_f32_e32 v6, v80, v140
	v_fmac_f32_e32 v7, v80, v144
	v_fmac_f32_e32 v4, v80, v148
	v_fmac_f32_e32 v5, v80, v152
	v_fmac_f32_e32 v2, v80, v156
	v_fmac_f32_e32 v3, v80, v160
	v_fmac_f32_e32 v13, v80, v164
	s_waitcnt vmcnt(48)
	v_fmac_f32_e32 v8, v81, v133
	v_fmac_f32_e32 v9, v81, v137
	v_fmac_f32_e32 v6, v81, v141
	v_fmac_f32_e32 v7, v81, v145
	v_fmac_f32_e32 v4, v81, v149
	v_fmac_f32_e32 v5, v81, v153
	v_fmac_f32_e32 v2, v81, v157
	v_fmac_f32_e32 v3, v81, v161
	v_fmac_f32_e32 v13, v81, v165
	s_waitcnt lgkmcnt(0)
	ds_read_b128 v[130:133], v65 offset:80
	ds_read_b128 v[134:137], v65 offset:336
	ds_read_b128 v[138:141], v65 offset:592
	ds_read_b128 v[142:145], v65 offset:848
	ds_read_b128 v[146:149], v65 offset:1104
	ds_read_b128 v[150:153], v65 offset:1360
	ds_read_b128 v[154:157], v65 offset:1616
	ds_read_b128 v[158:161], v65 offset:1872
	ds_read_b128 v[162:165], v65 offset:2128
	s_waitcnt vmcnt(47)
	v_fmac_f32_e32 v8, v82, v14
	v_fmac_f32_e32 v9, v82, v18
	v_fmac_f32_e32 v6, v82, v22
	v_fmac_f32_e32 v7, v82, v26
	v_fmac_f32_e32 v4, v82, v30
	v_fmac_f32_e32 v5, v82, v34
	v_fmac_f32_e32 v2, v82, v38
	v_fmac_f32_e32 v3, v82, v42
	v_fmac_f32_e32 v13, v82, v46
	s_waitcnt vmcnt(46)
	v_fmac_f32_e32 v8, v83, v15
	v_fmac_f32_e32 v9, v83, v19
	v_fmac_f32_e32 v6, v83, v23
	v_fmac_f32_e32 v7, v83, v27
	v_fmac_f32_e32 v4, v83, v31
	v_fmac_f32_e32 v5, v83, v35
	v_fmac_f32_e32 v2, v83, v39
	v_fmac_f32_e32 v3, v83, v43
	v_fmac_f32_e32 v13, v83, v47
	s_waitcnt vmcnt(45)
	v_fmac_f32_e32 v8, v84, v16
	v_fmac_f32_e32 v9, v84, v20
	v_fmac_f32_e32 v6, v84, v24
	v_fmac_f32_e32 v7, v84, v28
	v_fmac_f32_e32 v4, v84, v32
	v_fmac_f32_e32 v5, v84, v36
	v_fmac_f32_e32 v2, v84, v40
	v_fmac_f32_e32 v3, v84, v44
	v_fmac_f32_e32 v13, v84, v48
	s_waitcnt vmcnt(44)
	v_fmac_f32_e32 v8, v85, v17
	v_fmac_f32_e32 v9, v85, v21
	v_fmac_f32_e32 v6, v85, v25
	v_fmac_f32_e32 v7, v85, v29
	v_fmac_f32_e32 v4, v85, v33
	v_fmac_f32_e32 v5, v85, v37
	v_fmac_f32_e32 v2, v85, v41
	v_fmac_f32_e32 v3, v85, v45
	v_fmac_f32_e32 v13, v85, v49
	s_waitcnt lgkmcnt(0)
	ds_read_b128 v[14:17], v65 offset:96
	ds_read_b128 v[18:21], v65 offset:352
	ds_read_b128 v[22:25], v65 offset:608
	ds_read_b128 v[26:29], v65 offset:864
	ds_read_b128 v[30:33], v65 offset:1120
	ds_read_b128 v[34:37], v65 offset:1376
	ds_read_b128 v[38:41], v65 offset:1632
	ds_read_b128 v[42:45], v65 offset:1888
	ds_read_b128 v[46:49], v65 offset:2144
	s_waitcnt vmcnt(43)
	v_fmac_f32_e32 v8, v86, v130
	v_fmac_f32_e32 v9, v86, v134
	v_fmac_f32_e32 v6, v86, v138
	v_fmac_f32_e32 v7, v86, v142
	v_fmac_f32_e32 v4, v86, v146
	v_fmac_f32_e32 v5, v86, v150
	v_fmac_f32_e32 v2, v86, v154
	v_fmac_f32_e32 v3, v86, v158
	v_fmac_f32_e32 v13, v86, v162
	s_waitcnt vmcnt(42)
	v_fmac_f32_e32 v8, v87, v131
	v_fmac_f32_e32 v9, v87, v135
	v_fmac_f32_e32 v6, v87, v139
	v_fmac_f32_e32 v7, v87, v143
	v_fmac_f32_e32 v4, v87, v147
	v_fmac_f32_e32 v5, v87, v151
	v_fmac_f32_e32 v2, v87, v155
	v_fmac_f32_e32 v3, v87, v159
	v_fmac_f32_e32 v13, v87, v163
	s_waitcnt vmcnt(41)
	v_fmac_f32_e32 v8, v88, v132
	v_fmac_f32_e32 v9, v88, v136
	v_fmac_f32_e32 v6, v88, v140
	v_fmac_f32_e32 v7, v88, v144
	v_fmac_f32_e32 v4, v88, v148
	v_fmac_f32_e32 v5, v88, v152
	v_fmac_f32_e32 v2, v88, v156
	v_fmac_f32_e32 v3, v88, v160
	v_fmac_f32_e32 v13, v88, v164
	s_waitcnt vmcnt(40)
	v_fmac_f32_e32 v8, v89, v133
	v_fmac_f32_e32 v9, v89, v137
	v_fmac_f32_e32 v6, v89, v141
	v_fmac_f32_e32 v7, v89, v145
	v_fmac_f32_e32 v4, v89, v149
	v_fmac_f32_e32 v5, v89, v153
	v_fmac_f32_e32 v2, v89, v157
	v_fmac_f32_e32 v3, v89, v161
	v_fmac_f32_e32 v13, v89, v165
	s_waitcnt lgkmcnt(0)
	ds_read_b128 v[130:133], v65 offset:112
	ds_read_b128 v[134:137], v65 offset:368
	ds_read_b128 v[138:141], v65 offset:624
	ds_read_b128 v[142:145], v65 offset:880
	ds_read_b128 v[146:149], v65 offset:1136
	ds_read_b128 v[150:153], v65 offset:1392
	ds_read_b128 v[154:157], v65 offset:1648
	ds_read_b128 v[158:161], v65 offset:1904
	ds_read_b128 v[162:165], v65 offset:2160
	s_waitcnt vmcnt(39)
	v_fmac_f32_e32 v8, v90, v14
	v_fmac_f32_e32 v9, v90, v18
	v_fmac_f32_e32 v6, v90, v22
	v_fmac_f32_e32 v7, v90, v26
	v_fmac_f32_e32 v4, v90, v30
	v_fmac_f32_e32 v5, v90, v34
	v_fmac_f32_e32 v2, v90, v38
	v_fmac_f32_e32 v3, v90, v42
	v_fmac_f32_e32 v13, v90, v46
	s_waitcnt vmcnt(38)
	v_fmac_f32_e32 v8, v91, v15
	v_fmac_f32_e32 v9, v91, v19
	v_fmac_f32_e32 v6, v91, v23
	v_fmac_f32_e32 v7, v91, v27
	v_fmac_f32_e32 v4, v91, v31
	v_fmac_f32_e32 v5, v91, v35
	v_fmac_f32_e32 v2, v91, v39
	v_fmac_f32_e32 v3, v91, v43
	v_fmac_f32_e32 v13, v91, v47
	s_waitcnt vmcnt(37)
	v_fmac_f32_e32 v8, v92, v16
	v_fmac_f32_e32 v9, v92, v20
	v_fmac_f32_e32 v6, v92, v24
	v_fmac_f32_e32 v7, v92, v28
	v_fmac_f32_e32 v4, v92, v32
	v_fmac_f32_e32 v5, v92, v36
	v_fmac_f32_e32 v2, v92, v40
	v_fmac_f32_e32 v3, v92, v44
	v_fmac_f32_e32 v13, v92, v48
	s_waitcnt vmcnt(36)
	v_fmac_f32_e32 v8, v93, v17
	v_fmac_f32_e32 v9, v93, v21
	v_fmac_f32_e32 v6, v93, v25
	v_fmac_f32_e32 v7, v93, v29
	v_fmac_f32_e32 v4, v93, v33
	v_fmac_f32_e32 v5, v93, v37
	v_fmac_f32_e32 v2, v93, v41
	v_fmac_f32_e32 v3, v93, v45
	v_fmac_f32_e32 v13, v93, v49
	s_waitcnt lgkmcnt(0)
	ds_read_b128 v[14:17], v65 offset:128
	ds_read_b128 v[18:21], v65 offset:384
	ds_read_b128 v[22:25], v65 offset:640
	ds_read_b128 v[26:29], v65 offset:896
	ds_read_b128 v[30:33], v65 offset:1152
	ds_read_b128 v[34:37], v65 offset:1408
	ds_read_b128 v[38:41], v65 offset:1664
	ds_read_b128 v[42:45], v65 offset:1920
	ds_read_b128 v[46:49], v65 offset:2176
	s_waitcnt vmcnt(35)
	v_fmac_f32_e32 v8, v94, v130
	v_fmac_f32_e32 v9, v94, v134
	v_fmac_f32_e32 v6, v94, v138
	v_fmac_f32_e32 v7, v94, v142
	v_fmac_f32_e32 v4, v94, v146
	v_fmac_f32_e32 v5, v94, v150
	v_fmac_f32_e32 v2, v94, v154
	v_fmac_f32_e32 v3, v94, v158
	v_fmac_f32_e32 v13, v94, v162
	s_waitcnt vmcnt(34)
	v_fmac_f32_e32 v8, v95, v131
	v_fmac_f32_e32 v9, v95, v135
	v_fmac_f32_e32 v6, v95, v139
	v_fmac_f32_e32 v7, v95, v143
	v_fmac_f32_e32 v4, v95, v147
	v_fmac_f32_e32 v5, v95, v151
	v_fmac_f32_e32 v2, v95, v155
	v_fmac_f32_e32 v3, v95, v159
	v_fmac_f32_e32 v13, v95, v163
	s_waitcnt vmcnt(33)
	v_fmac_f32_e32 v8, v96, v132
	v_fmac_f32_e32 v9, v96, v136
	v_fmac_f32_e32 v6, v96, v140
	v_fmac_f32_e32 v7, v96, v144
	v_fmac_f32_e32 v4, v96, v148
	v_fmac_f32_e32 v5, v96, v152
	v_fmac_f32_e32 v2, v96, v156
	v_fmac_f32_e32 v3, v96, v160
	v_fmac_f32_e32 v13, v96, v164
	s_waitcnt vmcnt(32)
	v_fmac_f32_e32 v8, v97, v133
	v_fmac_f32_e32 v9, v97, v137
	v_fmac_f32_e32 v6, v97, v141
	v_fmac_f32_e32 v7, v97, v145
	v_fmac_f32_e32 v4, v97, v149
	v_fmac_f32_e32 v5, v97, v153
	v_fmac_f32_e32 v2, v97, v157
	v_fmac_f32_e32 v3, v97, v161
	v_fmac_f32_e32 v13, v97, v165
	s_waitcnt lgkmcnt(0)
	ds_read_b128 v[130:133], v65 offset:144
	ds_read_b128 v[134:137], v65 offset:400
	ds_read_b128 v[138:141], v65 offset:656
	ds_read_b128 v[142:145], v65 offset:912
	ds_read_b128 v[146:149], v65 offset:1168
	ds_read_b128 v[150:153], v65 offset:1424
	ds_read_b128 v[154:157], v65 offset:1680
	ds_read_b128 v[158:161], v65 offset:1936
	ds_read_b128 v[162:165], v65 offset:2192
	s_waitcnt vmcnt(31)
	v_fmac_f32_e32 v8, v98, v14
	v_fmac_f32_e32 v9, v98, v18
	v_fmac_f32_e32 v6, v98, v22
	v_fmac_f32_e32 v7, v98, v26
	v_fmac_f32_e32 v4, v98, v30
	v_fmac_f32_e32 v5, v98, v34
	v_fmac_f32_e32 v2, v98, v38
	v_fmac_f32_e32 v3, v98, v42
	v_fmac_f32_e32 v13, v98, v46
	s_waitcnt vmcnt(30)
	v_fmac_f32_e32 v8, v99, v15
	v_fmac_f32_e32 v9, v99, v19
	v_fmac_f32_e32 v6, v99, v23
	v_fmac_f32_e32 v7, v99, v27
	v_fmac_f32_e32 v4, v99, v31
	v_fmac_f32_e32 v5, v99, v35
	v_fmac_f32_e32 v2, v99, v39
	v_fmac_f32_e32 v3, v99, v43
	v_fmac_f32_e32 v13, v99, v47
	s_waitcnt vmcnt(29)
	v_fmac_f32_e32 v8, v100, v16
	v_fmac_f32_e32 v9, v100, v20
	v_fmac_f32_e32 v6, v100, v24
	v_fmac_f32_e32 v7, v100, v28
	v_fmac_f32_e32 v4, v100, v32
	v_fmac_f32_e32 v5, v100, v36
	v_fmac_f32_e32 v2, v100, v40
	v_fmac_f32_e32 v3, v100, v44
	v_fmac_f32_e32 v13, v100, v48
	s_waitcnt vmcnt(28)
	v_fmac_f32_e32 v8, v101, v17
	v_fmac_f32_e32 v9, v101, v21
	v_fmac_f32_e32 v6, v101, v25
	v_fmac_f32_e32 v7, v101, v29
	v_fmac_f32_e32 v4, v101, v33
	v_fmac_f32_e32 v5, v101, v37
	v_fmac_f32_e32 v2, v101, v41
	v_fmac_f32_e32 v3, v101, v45
	v_fmac_f32_e32 v13, v101, v49
	s_waitcnt lgkmcnt(0)
	ds_read_b128 v[14:17], v65 offset:160
	ds_read_b128 v[18:21], v65 offset:416
	ds_read_b128 v[22:25], v65 offset:672
	ds_read_b128 v[26:29], v65 offset:928
	ds_read_b128 v[30:33], v65 offset:1184
	ds_read_b128 v[34:37], v65 offset:1440
	ds_read_b128 v[38:41], v65 offset:1696
	ds_read_b128 v[42:45], v65 offset:1952
	ds_read_b128 v[46:49], v65 offset:2208
	s_waitcnt vmcnt(27)
	v_fmac_f32_e32 v8, v102, v130
	v_fmac_f32_e32 v9, v102, v134
	v_fmac_f32_e32 v6, v102, v138
	v_fmac_f32_e32 v7, v102, v142
	v_fmac_f32_e32 v4, v102, v146
	v_fmac_f32_e32 v5, v102, v150
	v_fmac_f32_e32 v2, v102, v154
	v_fmac_f32_e32 v3, v102, v158
	v_fmac_f32_e32 v13, v102, v162
	s_waitcnt vmcnt(26)
	v_fmac_f32_e32 v8, v103, v131
	v_fmac_f32_e32 v9, v103, v135
	v_fmac_f32_e32 v6, v103, v139
	v_fmac_f32_e32 v7, v103, v143
	v_fmac_f32_e32 v4, v103, v147
	v_fmac_f32_e32 v5, v103, v151
	v_fmac_f32_e32 v2, v103, v155
	v_fmac_f32_e32 v3, v103, v159
	v_fmac_f32_e32 v13, v103, v163
	s_waitcnt vmcnt(25)
	v_fmac_f32_e32 v8, v104, v132
	v_fmac_f32_e32 v9, v104, v136
	v_fmac_f32_e32 v6, v104, v140
	v_fmac_f32_e32 v7, v104, v144
	v_fmac_f32_e32 v4, v104, v148
	v_fmac_f32_e32 v5, v104, v152
	v_fmac_f32_e32 v2, v104, v156
	v_fmac_f32_e32 v3, v104, v160
	v_fmac_f32_e32 v13, v104, v164
	s_waitcnt vmcnt(24)
	v_fmac_f32_e32 v8, v105, v133
	v_fmac_f32_e32 v9, v105, v137
	v_fmac_f32_e32 v6, v105, v141
	v_fmac_f32_e32 v7, v105, v145
	v_fmac_f32_e32 v4, v105, v149
	v_fmac_f32_e32 v5, v105, v153
	v_fmac_f32_e32 v2, v105, v157
	v_fmac_f32_e32 v3, v105, v161
	v_fmac_f32_e32 v13, v105, v165
	s_waitcnt lgkmcnt(0)
	ds_read_b128 v[130:133], v65 offset:176
	ds_read_b128 v[134:137], v65 offset:432
	ds_read_b128 v[138:141], v65 offset:688
	ds_read_b128 v[142:145], v65 offset:944
	ds_read_b128 v[146:149], v65 offset:1200
	ds_read_b128 v[150:153], v65 offset:1456
	ds_read_b128 v[154:157], v65 offset:1712
	ds_read_b128 v[158:161], v65 offset:1968
	ds_read_b128 v[162:165], v65 offset:2224
	s_waitcnt vmcnt(23)
	v_fmac_f32_e32 v8, v106, v14
	v_fmac_f32_e32 v9, v106, v18
	v_fmac_f32_e32 v6, v106, v22
	v_fmac_f32_e32 v7, v106, v26
	v_fmac_f32_e32 v4, v106, v30
	v_fmac_f32_e32 v5, v106, v34
	v_fmac_f32_e32 v2, v106, v38
	v_fmac_f32_e32 v3, v106, v42
	v_fmac_f32_e32 v13, v106, v46
	s_waitcnt vmcnt(22)
	v_fmac_f32_e32 v8, v107, v15
	v_fmac_f32_e32 v9, v107, v19
	v_fmac_f32_e32 v6, v107, v23
	v_fmac_f32_e32 v7, v107, v27
	v_fmac_f32_e32 v4, v107, v31
	v_fmac_f32_e32 v5, v107, v35
	v_fmac_f32_e32 v2, v107, v39
	v_fmac_f32_e32 v3, v107, v43
	v_fmac_f32_e32 v13, v107, v47
	s_waitcnt vmcnt(21)
	v_fmac_f32_e32 v8, v108, v16
	v_fmac_f32_e32 v9, v108, v20
	v_fmac_f32_e32 v6, v108, v24
	v_fmac_f32_e32 v7, v108, v28
	v_fmac_f32_e32 v4, v108, v32
	v_fmac_f32_e32 v5, v108, v36
	v_fmac_f32_e32 v2, v108, v40
	v_fmac_f32_e32 v3, v108, v44
	v_fmac_f32_e32 v13, v108, v48
	s_waitcnt vmcnt(20)
	v_fmac_f32_e32 v8, v109, v17
	v_fmac_f32_e32 v9, v109, v21
	v_fmac_f32_e32 v6, v109, v25
	v_fmac_f32_e32 v7, v109, v29
	v_fmac_f32_e32 v4, v109, v33
	v_fmac_f32_e32 v5, v109, v37
	v_fmac_f32_e32 v2, v109, v41
	v_fmac_f32_e32 v3, v109, v45
	v_fmac_f32_e32 v13, v109, v49
	s_waitcnt lgkmcnt(0)
	ds_read_b128 v[14:17], v65 offset:192
	ds_read_b128 v[18:21], v65 offset:448
	ds_read_b128 v[22:25], v65 offset:704
	ds_read_b128 v[26:29], v65 offset:960
	ds_read_b128 v[30:33], v65 offset:1216
	ds_read_b128 v[34:37], v65 offset:1472
	ds_read_b128 v[38:41], v65 offset:1728
	ds_read_b128 v[42:45], v65 offset:1984
	ds_read_b128 v[46:49], v65 offset:2240
	s_waitcnt vmcnt(19)
	v_fmac_f32_e32 v8, v110, v130
	v_fmac_f32_e32 v9, v110, v134
	v_fmac_f32_e32 v6, v110, v138
	v_fmac_f32_e32 v7, v110, v142
	v_fmac_f32_e32 v4, v110, v146
	v_fmac_f32_e32 v5, v110, v150
	v_fmac_f32_e32 v2, v110, v154
	v_fmac_f32_e32 v3, v110, v158
	v_fmac_f32_e32 v13, v110, v162
	s_waitcnt vmcnt(18)
	v_fmac_f32_e32 v8, v111, v131
	v_fmac_f32_e32 v9, v111, v135
	v_fmac_f32_e32 v6, v111, v139
	v_fmac_f32_e32 v7, v111, v143
	v_fmac_f32_e32 v4, v111, v147
	v_fmac_f32_e32 v5, v111, v151
	v_fmac_f32_e32 v2, v111, v155
	v_fmac_f32_e32 v3, v111, v159
	v_fmac_f32_e32 v13, v111, v163
	s_waitcnt vmcnt(17)
	v_fmac_f32_e32 v8, v112, v132
	v_fmac_f32_e32 v9, v112, v136
	v_fmac_f32_e32 v6, v112, v140
	v_fmac_f32_e32 v7, v112, v144
	v_fmac_f32_e32 v4, v112, v148
	v_fmac_f32_e32 v5, v112, v152
	v_fmac_f32_e32 v2, v112, v156
	v_fmac_f32_e32 v3, v112, v160
	v_fmac_f32_e32 v13, v112, v164
	s_waitcnt vmcnt(16)
	v_fmac_f32_e32 v8, v113, v133
	v_fmac_f32_e32 v9, v113, v137
	v_fmac_f32_e32 v6, v113, v141
	v_fmac_f32_e32 v7, v113, v145
	v_fmac_f32_e32 v4, v113, v149
	v_fmac_f32_e32 v5, v113, v153
	v_fmac_f32_e32 v2, v113, v157
	v_fmac_f32_e32 v3, v113, v161
	v_fmac_f32_e32 v13, v113, v165
	s_waitcnt lgkmcnt(0)
	ds_read_b128 v[130:133], v65 offset:208
	ds_read_b128 v[134:137], v65 offset:464
	ds_read_b128 v[138:141], v65 offset:720
	ds_read_b128 v[142:145], v65 offset:976
	ds_read_b128 v[146:149], v65 offset:1232
	ds_read_b128 v[150:153], v65 offset:1488
	ds_read_b128 v[154:157], v65 offset:1744
	ds_read_b128 v[158:161], v65 offset:2000
	ds_read_b128 v[162:165], v65 offset:2256
	s_waitcnt vmcnt(15)
	v_fmac_f32_e32 v8, v114, v14
	v_fmac_f32_e32 v9, v114, v18
	v_fmac_f32_e32 v6, v114, v22
	v_fmac_f32_e32 v7, v114, v26
	v_fmac_f32_e32 v4, v114, v30
	v_fmac_f32_e32 v5, v114, v34
	v_fmac_f32_e32 v2, v114, v38
	v_fmac_f32_e32 v3, v114, v42
	v_fmac_f32_e32 v13, v114, v46
	s_waitcnt vmcnt(14)
	v_fmac_f32_e32 v8, v115, v15
	v_fmac_f32_e32 v9, v115, v19
	v_fmac_f32_e32 v6, v115, v23
	v_fmac_f32_e32 v7, v115, v27
	v_fmac_f32_e32 v4, v115, v31
	v_fmac_f32_e32 v5, v115, v35
	v_fmac_f32_e32 v2, v115, v39
	v_fmac_f32_e32 v3, v115, v43
	v_fmac_f32_e32 v13, v115, v47
	s_waitcnt vmcnt(13)
	v_fmac_f32_e32 v8, v116, v16
	v_fmac_f32_e32 v9, v116, v20
	v_fmac_f32_e32 v6, v116, v24
	v_fmac_f32_e32 v7, v116, v28
	v_fmac_f32_e32 v4, v116, v32
	v_fmac_f32_e32 v5, v116, v36
	v_fmac_f32_e32 v2, v116, v40
	v_fmac_f32_e32 v3, v116, v44
	v_fmac_f32_e32 v13, v116, v48
	s_waitcnt vmcnt(12)
	v_fmac_f32_e32 v8, v117, v17
	v_fmac_f32_e32 v9, v117, v21
	v_fmac_f32_e32 v6, v117, v25
	v_fmac_f32_e32 v7, v117, v29
	v_fmac_f32_e32 v4, v117, v33
	v_fmac_f32_e32 v5, v117, v37
	v_fmac_f32_e32 v2, v117, v41
	v_fmac_f32_e32 v3, v117, v45
	v_fmac_f32_e32 v13, v117, v49
	s_waitcnt lgkmcnt(0)
	ds_read_b128 v[14:17], v65 offset:224
	ds_read_b128 v[18:21], v65 offset:480
	ds_read_b128 v[22:25], v65 offset:736
	ds_read_b128 v[26:29], v65 offset:992
	ds_read_b128 v[30:33], v65 offset:1248
	ds_read_b128 v[34:37], v65 offset:1504
	ds_read_b128 v[38:41], v65 offset:1760
	ds_read_b128 v[42:45], v65 offset:2016
	ds_read_b128 v[46:49], v65 offset:2272
	s_waitcnt vmcnt(11)
	v_fmac_f32_e32 v8, v118, v130
	v_fmac_f32_e32 v9, v118, v134
	v_fmac_f32_e32 v6, v118, v138
	v_fmac_f32_e32 v7, v118, v142
	v_fmac_f32_e32 v4, v118, v146
	v_fmac_f32_e32 v5, v118, v150
	v_fmac_f32_e32 v2, v118, v154
	v_fmac_f32_e32 v3, v118, v158
	v_fmac_f32_e32 v13, v118, v162
	s_waitcnt vmcnt(10)
	v_fmac_f32_e32 v8, v119, v131
	v_fmac_f32_e32 v9, v119, v135
	v_fmac_f32_e32 v6, v119, v139
	v_fmac_f32_e32 v7, v119, v143
	v_fmac_f32_e32 v4, v119, v147
	v_fmac_f32_e32 v5, v119, v151
	v_fmac_f32_e32 v2, v119, v155
	v_fmac_f32_e32 v3, v119, v159
	v_fmac_f32_e32 v13, v119, v163
	s_waitcnt vmcnt(9)
	v_fmac_f32_e32 v8, v120, v132
	v_fmac_f32_e32 v9, v120, v136
	v_fmac_f32_e32 v6, v120, v140
	v_fmac_f32_e32 v7, v120, v144
	v_fmac_f32_e32 v4, v120, v148
	v_fmac_f32_e32 v5, v120, v152
	v_fmac_f32_e32 v2, v120, v156
	v_fmac_f32_e32 v3, v120, v160
	v_fmac_f32_e32 v13, v120, v164
	s_waitcnt vmcnt(8)
	v_fmac_f32_e32 v8, v121, v133
	v_fmac_f32_e32 v9, v121, v137
	v_fmac_f32_e32 v6, v121, v141
	v_fmac_f32_e32 v7, v121, v145
	v_fmac_f32_e32 v4, v121, v149
	v_fmac_f32_e32 v5, v121, v153
	v_fmac_f32_e32 v2, v121, v157
	v_fmac_f32_e32 v3, v121, v161
	v_fmac_f32_e32 v13, v121, v165
	s_waitcnt lgkmcnt(0)
	ds_read_b128 v[130:133], v65 offset:240
	ds_read_b128 v[134:137], v65 offset:496
	ds_read_b128 v[138:141], v65 offset:752
	ds_read_b128 v[142:145], v65 offset:1008
	ds_read_b128 v[146:149], v65 offset:1264
	ds_read_b128 v[150:153], v65 offset:1520
	ds_read_b128 v[154:157], v65 offset:1776
	ds_read_b128 v[158:161], v65 offset:2032
	ds_read_b128 v[162:165], v65 offset:2288
	s_waitcnt vmcnt(7)
	v_fmac_f32_e32 v8, v122, v14
	v_fmac_f32_e32 v9, v122, v18
	v_fmac_f32_e32 v6, v122, v22
	v_fmac_f32_e32 v7, v122, v26
	v_fmac_f32_e32 v4, v122, v30
	v_fmac_f32_e32 v5, v122, v34
	v_fmac_f32_e32 v2, v122, v38
	v_fmac_f32_e32 v3, v122, v42
	v_fmac_f32_e32 v13, v122, v46
	s_waitcnt vmcnt(6)
	v_fmac_f32_e32 v8, v123, v15
	v_fmac_f32_e32 v9, v123, v19
	v_fmac_f32_e32 v6, v123, v23
	v_fmac_f32_e32 v7, v123, v27
	v_fmac_f32_e32 v4, v123, v31
	v_fmac_f32_e32 v5, v123, v35
	v_fmac_f32_e32 v2, v123, v39
	v_fmac_f32_e32 v3, v123, v43
	v_fmac_f32_e32 v13, v123, v47
	s_waitcnt vmcnt(5)
	v_fmac_f32_e32 v8, v124, v16
	v_fmac_f32_e32 v9, v124, v20
	v_fmac_f32_e32 v6, v124, v24
	v_fmac_f32_e32 v7, v124, v28
	v_fmac_f32_e32 v4, v124, v32
	v_fmac_f32_e32 v5, v124, v36
	v_fmac_f32_e32 v2, v124, v40
	v_fmac_f32_e32 v3, v124, v44
	v_fmac_f32_e32 v13, v124, v48
	s_waitcnt vmcnt(4)
	v_fmac_f32_e32 v8, v125, v17
	v_fmac_f32_e32 v9, v125, v21
	v_fmac_f32_e32 v6, v125, v25
	v_fmac_f32_e32 v7, v125, v29
	v_fmac_f32_e32 v4, v125, v33
	v_fmac_f32_e32 v5, v125, v37
	v_fmac_f32_e32 v2, v125, v41
	v_fmac_f32_e32 v3, v125, v45
	v_fmac_f32_e32 v13, v125, v49
	s_waitcnt lgkmcnt(0)
	s_waitcnt vmcnt(3)
	v_fmac_f32_e32 v8, v126, v130
	v_fmac_f32_e32 v9, v126, v134
	v_fmac_f32_e32 v6, v126, v138
	v_fmac_f32_e32 v7, v126, v142
	v_fmac_f32_e32 v4, v126, v146
	v_fmac_f32_e32 v5, v126, v150
	v_fmac_f32_e32 v2, v126, v154
	v_fmac_f32_e32 v3, v126, v158
	v_fmac_f32_e32 v13, v126, v162
	s_waitcnt vmcnt(2)
	v_fmac_f32_e32 v8, v127, v131
	v_fmac_f32_e32 v9, v127, v135
	v_fmac_f32_e32 v6, v127, v139
	v_fmac_f32_e32 v7, v127, v143
	v_fmac_f32_e32 v4, v127, v147
	v_fmac_f32_e32 v5, v127, v151
	v_fmac_f32_e32 v2, v127, v155
	v_fmac_f32_e32 v3, v127, v159
	v_fmac_f32_e32 v13, v127, v163
	s_waitcnt vmcnt(1)
	v_fmac_f32_e32 v8, v128, v132
	v_fmac_f32_e32 v9, v128, v136
	v_fmac_f32_e32 v6, v128, v140
	v_fmac_f32_e32 v7, v128, v144
	v_fmac_f32_e32 v4, v128, v148
	v_fmac_f32_e32 v5, v128, v152
	v_fmac_f32_e32 v2, v128, v156
	v_fmac_f32_e32 v3, v128, v160
	v_fmac_f32_e32 v13, v128, v164
	s_waitcnt vmcnt(0)
	v_fmac_f32_e32 v8, v129, v133
	v_fmac_f32_e32 v9, v129, v137
	v_fmac_f32_e32 v6, v129, v141
	v_fmac_f32_e32 v7, v129, v145
	v_fmac_f32_e32 v4, v129, v149
	v_fmac_f32_e32 v5, v129, v153
	v_fmac_f32_e32 v2, v129, v157
	v_fmac_f32_e32 v3, v129, v161
	v_fmac_f32_e32 v13, v129, v165
	s_ashr_i32 s6, s20, 6
	s_add_i32 s6, s6, s21
	s_lshl_b32 s6, s6, 4
	s_add_i32 s6, s6, s22
	s_mul_hi_i32 s7, s6, 0x51000
	s_mul_i32 s6, s6, 0x51000
	s_add_u32 s6, s9, s6
	s_addc_u32 s7, s10, s7
	s_add_u32 s4, s6, s4
	s_addc_u32 s5, s7, s5
	v_lshl_add_u64 v[10:11], v[0:1], 2, s[4:5]
	v_add_co_u32_e32 v14, vcc, s13, v10
	global_store_dword v[10:11], v8, off
	s_nop 0
	v_addc_co_u32_e32 v15, vcc, 0, v11, vcc
	v_add_co_u32_e32 v8, vcc, s14, v10
	global_store_dword v[14:15], v9, off
	s_nop 0
	v_addc_co_u32_e32 v9, vcc, 0, v11, vcc
	global_store_dword v[8:9], v6, off
	v_add_co_u32_e32 v8, vcc, s15, v10
	s_add_i32 s19, s19, s26
	s_nop 0
	v_addc_co_u32_e32 v9, vcc, 0, v11, vcc
	v_add_co_u32_e32 v6, vcc, s16, v10
	global_store_dword v[8:9], v7, off
	s_nop 0
	v_addc_co_u32_e32 v7, vcc, 0, v11, vcc
	global_store_dword v[6:7], v4, off
	v_add_co_u32_e32 v6, vcc, s17, v10
	s_cmpk_gt_i32 s19, 0x23f
	s_nop 0
	v_addc_co_u32_e32 v7, vcc, 0, v11, vcc
	v_add_co_u32_e32 v4, vcc, s18, v10
	global_store_dword v[6:7], v5, off
	s_nop 0
	v_addc_co_u32_e32 v5, vcc, 0, v11, vcc
	global_store_dword v[4:5], v2, off
	v_add_co_u32_e32 v4, vcc, 0x3f000, v10
	s_nop 1
	v_addc_co_u32_e32 v5, vcc, 0, v11, vcc
	v_add_co_u32_e32 v2, vcc, 0x48000, v10
	global_store_dword v[4:5], v3, off
	s_nop 0
	v_addc_co_u32_e32 v3, vcc, 0, v11, vcc
	global_store_dword v[2:3], v13, off
	s_cbranch_scc0 .LBB0_19
